# attention V^T staging: 8 ds_write_b16 per lane -> 4 ds_write_b32 via adjacent-lane exchange (v_cndmask_b32_dpp) and 16-bit packing, same LDS bytes
# speedup vs baseline: 1.0056x; 1.0020x over previous
; #define SEAM(k) do { if (IN(k) && IN((k) + 1)) { if ((k) == 0) cg::this_grid().sync(); else xcd_barrier(xbar); } } while (0)
; #define REP(k) for (int rep_ = 0; rep_ < ((((REPMASK) >> (k)) & 1) ? 2 : 1); ++rep_, (((REPMASK) >> (k)) & 1) ? cg::this_grid().sync() : (void)0)
;     const int tid = threadIdx.x, lane = tid & 63, w = __builtin_amdgcn_readfirstlane(tid >> 6), r32 = lane & 31, hi = lane >> 5;
;     constexpr int KS = 144, VS = 136, KBYTES = 64 * KS, VBYTES = 64 * VS, VOFF = 2 * KBYTES;
;     const bf16_t* QKV = (const bf16_t*)(a.ws + WS_QKV); bf16_t* OB = (bf16_t*)(a.ws + WS_OB); const float* ROPE = (const float*)(a.ws + WS_ROPE);
;     const float* qgain = a.in[10]; const float* sink = a.in[12];
;     const float C2 = 0.125f * 1.4426950408889634f;
;     const int krow = w * 8 + (lane >> 3), kch = lane & 7;
;     for (int unit = vcu; unit < 4096; unit += G) {
;         const int b = unit >> 9, kvh = (unit >> 7) & 3, qb = unit & 127, q0 = qb * 64;
;         const int head = kvh * 4 + (w & 3), qrow = q0 + 32 * (w >> 2) + r32;
;         const int jlo = (q0 < 128) ? ((128 - q0) >> 6) : 0; const int jhi = (q0 > SEQ - 192) ? ((SEQ + 64 - q0) >> 6) : 4; const int ntiles = 4 + (jhi - jlo + 1);
; __global__ void __launch_bounds__(512, 2) fwd_megakernel(Args a) {
;     ...
;     if (IN(4)) REP(4) { attn_phase4<3>(L, a, vcu, G); } SEAM(4);
.LBB0_499:
	s_cmp_lt_i32 s30, 5
	s_cselect_b64 s[4:5], -1, 0
	s_and_b64 s[0:1], s[4:5], s[0:1]
	s_andn2_b64 vcc, exec, s[0:1]
	s_cbranch_vccnz .LBB0_526
	s_cmpk_gt_i32 s96, 0xfff
	v_readfirstlane_b32 s8, v152
	s_cbranch_scc1 .LBB0_526
	s_add_u32 s4, s28, 0xfa00000
	s_addc_u32 s5, s29, 0
	v_and_b32_e32 v5, 31, v152
	s_movk_i32 s10, 0x90
	s_add_u32 s6, s28, 0x1c000000
	v_bfe_u32 v3, v152, 5, 1
	v_mad_u32_u24 v6, v5, s10, 0
	s_addc_u32 s7, s29, 0
	v_and_b32_e32 v1, 7, v152
	v_lshlrev_b32_e32 v0, 3, v3
	v_lshl_add_u32 v145, v3, 4, v6
	v_lshlrev_b32_e32 v4, 2, v3
	v_lshlrev_b32_e32 v3, 3, v5
	s_lshr_b32 s20, s8, 6
	v_lshlrev_b32_e32 v2, 3, v1
	v_sub_u32_e32 v3, v6, v3
	v_lshlrev_b32_e32 v6, 4, v1
	v_bfe_u32 v1, v152, 3, 3
	s_lshl_b32 s21, s20, 3
	v_or_b32_e32 v154, s21, v1
	s_bfe_u32 s11, s8, 0x20006
	s_lshr_b32 s8, s8, 3
	v_mbcnt_lo_u32_b32 v1, -1, 0
	s_and_b32 s8, s8, 0x1fffffe0
	v_mbcnt_hi_u32_b32 v1, -1, v1
	v_and_b32_e32 v144, 63, v152
	v_or_b32_e32 v175, s8, v5
	v_and_b32_e32 v5, 64, v1
	v_add_u32_e32 v174, v3, v0
	v_cmp_gt_u32_e32 vcc, 32, v144
	v_xor_b32_e32 v3, 32, v1
	v_add_u32_e32 v5, 64, v5
	s_mul_i32 s8, s20, 0x440
	v_cndmask_b32_e64 v151, 0, 1.0, vcc
	v_cmp_lt_i32_e32 vcc, v3, v5
	s_add_i32 s8, s8, 0
	v_mov_b32_e32 v147, 0
	v_and_b32_e32 v146, 32, v152
	v_cndmask_b32_e32 v1, v1, v3, vcc
	v_lshl_add_u32 v178, v144, 1, s8
	s_lshl_b32 s8, s20, 4
	s_mov_b64 s[34:35], s[66:67]
	v_readlane_b32 s52, v255, 4
	v_lshlrev_b32_e32 v176, 2, v1
	v_mul_lo_u32 v1, v154, s10
	v_lshl_add_u64 v[8:9], s[28:29], 0, v[146:147]
	s_mov_b64 s[12:13], 0x100000
	s_add_u32 s42, s4, s8
	s_mov_b32 s9, 0
	v_readlane_b32 s53, v255, 5
	v_readlane_b32 s54, v255, 6
	v_readlane_b32 s55, v255, 7
	v_readlane_b32 s56, v255, 8
	v_readlane_b32 s57, v255, 9
	v_add3_u32 v177, 0, v6, v1
	v_lshl_add_u64 v[156:157], v[8:9], 0, s[12:13]
	v_mov_b32_e32 v7, v147
	s_addc_u32 s43, s5, 0
	v_sub_u32_e32 v1, v175, v4
	v_lshlrev_b32_e32 v164, 1, v2
	s_lshl_b32 s12, s21, 1
	v_lshl_add_u64 v[148:149], s[56:57], 0, v[146:147]
	v_mov_b32_e32 v155, v147
	v_mov_b32_e32 v150, v147
	v_lshl_add_u64 v[158:159], s[4:5], 0, v[6:7]
	s_lshl_b32 s44, s96, 6
	s_lshl_b32 s45, s3, 6
	v_add_u32_e32 v179, 0x84, v1
	s_movk_i32 s46, 0xc00
	v_mov_b64_e32 v[160:161], s[4:5]
	v_lshlrev_b32_e32 v162, 1, v0
	v_mov_b32_e32 v163, v147
	v_mov_b32_e32 v180, 0x358637bd
	s_mov_b32 s47, 0x800000
	s_mov_b32 s10, 0x3e38aa3b
	s_mov_b32 s20, s12
	s_mov_b32 s21, s9
	s_mov_b32 s52, 0x41000000
	s_movk_i32 s53, 0xfefe
	s_mov_b32 s54, 0xffff
	v_lshlrev_b32_e32 v166, 1, v4
	v_mov_b32_e32 v168, v164
	v_mov_b32_e32 v169, v147
	v_mov_b32_e32 v181, 0xff800000
	s_mov_b32 s55, s96
	v_readlane_b32 s58, v255, 10
	v_readlane_b32 s59, v255, 11
	v_readlane_b32 s60, v255, 12
	v_readlane_b32 s61, v255, 13
	v_readlane_b32 s62, v255, 14
	v_readlane_b32 s63, v255, 15
	v_readlane_b32 s64, v255, 16
	v_readlane_b32 s65, v255, 17
	v_readlane_b32 s66, v255, 18
	v_readlane_b32 s67, v255, 19
	s_mov_b32 s88, 0x55555555
	s_mov_b32 s89, 0x55555555
	s_mov_b32 s90, 0xaaaaaaaa
	s_mov_b32 s91, 0xaaaaaaaa
	s_mov_b32 s70, 0xffff0000
	s_branch .LBB0_503

; __device__ __forceinline__ float bf_lo(unsigned w) { return __uint_as_float(w << 16); }
; __device__ __forceinline__ float bf_hi(unsigned w) { return __uint_as_float(w & 0xffff0000u); }
; #define LOAD_TILE(ti, kreg, vreg) do { const int k0_ = TILE_K0(ti); const size_t grow_ = ((ti) < 4) ? (size_t)(M_ + b * LCTX + k0_) : (size_t)(b * SEQ + k0_); \
;         kreg = *(const u32x4*)(QKV + (grow_ + krow) * NQKV + 1024 + kvh * 64 + 8 * kch); vreg = *(const u32x4*)(QKV + (grow_ + lane) * NQKV + 1280 + kvh * 64 + 8 * w); } while (0)
; #define LOAD_TILE(ti, kreg, vreg) do { const int k0_ = TILE_K0(ti); const size_t grow_ = ((ti) < 4) ? (size_t)(M_ + b * LCTX + k0_) : (size_t)(b * SEQ + k0_); \
;         kreg = *(const u32x4*)(QKV + (grow_ + krow) * NQKV + 1024 + kvh * 64 + 8 * kch); vreg = *(const u32x4*)(QKV + (grow_ + lane) * NQKV + 1280 + kvh * 64 + 8 * w); } while (0)
;     ...
;             const bf16_t* qp = QKV + (size_t)(b * SEQ + qrow) * NQKV + head * 64;
;             float qf[4][8]; float ss = 0.f;
; #pragma unroll
;             for (int d0 = 0; d0 < 4; ++d0) { const u32x4 v = *(const u32x4*)(qp + 8 * (2 * d0 + hi));
;                 qf[d0][0] = bf_lo(v.x); qf[d0][1] = bf_hi(v.x); qf[d0][2] = bf_lo(v.y); qf[d0][3] = bf_hi(v.y); qf[d0][4] = bf_lo(v.z); qf[d0][5] = bf_hi(v.z); qf[d0][6] = bf_lo(v.w); qf[d0][7] = bf_hi(v.w);
; #pragma unroll
;                 for (int i = 0; i < 8; ++i) ss += qf[d0][i] * qf[d0][i]; }
;             ss += __shfl_xor(ss, 32);
;     ...
;         LOAD_TILE(0, kreg, vreg); STORE_TILE(0, 0); LOAD_TILE(1, kreg, vreg); LOAD_TILE(2, kreg2, vreg2); LOAD_TILE(3, kreg3, vreg3); __syncthreads();
.LBB0_503:
	s_lshl_b32 s8, s55, 6
	s_ashr_i32 s22, s55, 9
	s_bfe_u32 s25, s55, 0x20007
	s_and_b32 s13, s8, 0x1fc0
	s_lshl_b32 s8, s25, 2
	v_add_u32_e32 v146, s13, v175
	s_lshl_b32 s24, s22, 13
	s_or_b32 s38, s8, s11
	v_add_u32_e32 v170, s24, v146
	v_mad_i64_i32 v[0:1], s[40:41], v170, s46, v[160:161]
	s_lshl_b32 s8, s38, 7
	v_lshl_add_u64 v[0:1], v[0:1], 0, s[8:9]
	v_lshl_add_u64 v[0:1], v[0:1], 0, v[162:163]
	global_load_dwordx4 v[40:43], v[0:1], off offset:32
	global_load_dwordx4 v[44:47], v[0:1], off offset:96
	global_load_dwordx4 v[32:35], v[0:1], off
	global_load_dwordx4 v[28:31], v[0:1], off offset:64
	global_load_dwordx4 v[8:11], v[148:149], off offset:80
	global_load_dwordx4 v[12:15], v[148:149], off offset:64
	s_nop 0
	global_load_dwordx4 v[0:3], v[148:149], off offset:208
	global_load_dwordx4 v[4:7], v[148:149], off offset:192
	global_load_dwordx4 v[24:27], v[148:149], off offset:16
	global_load_dwordx4 v[36:39], v[148:149], off
	global_load_dwordx4 v[16:19], v[148:149], off offset:144
	s_waitcnt lgkmcnt(0)
	global_load_dwordx4 v[20:23], v[148:149], off offset:128
	v_lshlrev_b64 v[48:49], 8, v[146:147]
	s_lshl_b32 s8, s38, 2
	v_readlane_b32 s72, v255, 4
	v_lshl_add_u64 v[72:73], v[156:157], 0, v[48:49]
	v_mov_b32_e32 v76, s8
	v_readlane_b32 s80, v255, 12
	v_readlane_b32 s81, v255, 13
	global_load_dwordx4 v[48:51], v[72:73], off offset:64
	global_load_dwordx4 v[52:55], v[72:73], off offset:192
	global_load_dwordx4 v[56:59], v[72:73], off offset:16
	global_load_dwordx4 v[60:63], v[72:73], off
	global_load_dwordx4 v[64:67], v[72:73], off offset:144
	global_load_dwordx4 v[68:71], v[72:73], off offset:128
	global_load_dword v124, v76, s[80:81]
	s_lshl_b32 s39, s22, 8
	s_add_i32 s22, s39, 0x10000
	s_ashr_i32 s23, s22, 31
	v_lshl_add_u64 v[74:75], s[22:23], 0, v[154:155]
	s_lshl_b32 s8, s25, 7
	v_readlane_b32 s73, v255, 5
	v_readlane_b32 s74, v255, 6
	v_readlane_b32 s75, v255, 7
	v_readlane_b32 s76, v255, 8
	v_readlane_b32 s77, v255, 9
	v_readlane_b32 s78, v255, 10
	v_readlane_b32 s79, v255, 11
	v_readlane_b32 s82, v255, 14
	v_readlane_b32 s83, v255, 15
	v_readlane_b32 s84, v255, 16
	v_readlane_b32 s85, v255, 17
	v_readlane_b32 s86, v255, 18
	v_readlane_b32 s87, v255, 19
	v_mad_u64_u32 v[190:191], s[40:41], v74, s46, v[160:161]
	v_mad_i32_i24 v191, v75, s46, v191
	v_lshl_add_u64 v[190:191], v[190:191], 0, s[8:9]
	v_or_b32_e32 v242, s22, v144
	v_mad_i64_i32 v[242:243], s[40:41], v242, s46, v[160:161]
	v_lshl_add_u64 v[242:243], v[242:243], 0, s[8:9]
	v_lshl_add_u64 v[190:191], v[190:191], 0, v[168:169]
	v_lshl_add_u64 v[242:243], v[242:243], 0, s[20:21]
	global_load_dwordx4 v[244:247], v[190:191], off offset:2048
	global_load_dwordx4 v[248:251], v[242:243], off offset:2560
	s_waitcnt vmcnt(0)
	v_lshlrev_b32_e32 v86, 16, v40
	v_and_b32_e32 v87, 0xffff0000, v40
	v_lshlrev_b32_e32 v100, 16, v32
	v_and_b32_e32 v101, 0xffff0000, v32
	v_lshlrev_b32_e32 v96, 16, v33
	v_and_b32_e32 v97, 0xffff0000, v33
	v_pk_mul_f32 v[120:121], v[100:101], v[100:101]
	v_pk_mul_f32 v[116:117], v[96:97], v[96:97]
	v_add_f32_e32 v120, v120, v121
	v_lshlrev_b32_e32 v92, 16, v34
	v_and_b32_e32 v93, 0xffff0000, v34
	v_add_f32_e32 v116, v116, v120
	v_pk_mul_f32 v[112:113], v[92:93], v[92:93]
	v_add_f32_e32 v116, v117, v116
	v_lshlrev_b32_e32 v88, 16, v35
	v_and_b32_e32 v89, 0xffff0000, v35
	v_add_f32_e32 v112, v112, v116
	v_pk_mul_f32 v[108:109], v[88:89], v[88:89]
	v_add_f32_e32 v112, v113, v112
	v_add_f32_e32 v108, v108, v112
	v_pk_mul_f32 v[104:105], v[86:87], v[86:87]
	v_add_f32_e32 v108, v109, v108
	v_lshlrev_b32_e32 v78, 16, v47
	v_and_b32_e32 v79, 0xffff0000, v47
	v_lshlrev_b32_e32 v82, 16, v46
	v_and_b32_e32 v83, 0xffff0000, v46
	v_lshlrev_b32_e32 v46, 16, v41
	v_and_b32_e32 v47, 0xffff0000, v41
	v_add_f32_e32 v104, v104, v108
	v_lshlrev_b32_e32 v76, 16, v43
	v_and_b32_e32 v77, 0xffff0000, v43
	v_lshlrev_b32_e32 v80, 16, v42
	v_and_b32_e32 v81, 0xffff0000, v42
	v_pk_mul_f32 v[42:43], v[46:47], v[46:47]
	v_add_f32_e32 v104, v105, v104
	v_add_f32_e32 v42, v42, v104
	v_pk_mul_f32 v[32:33], v[80:81], v[80:81]
	v_add_f32_e32 v42, v43, v42
	v_add_f32_e32 v32, v32, v42
	v_lshlrev_b32_e32 v98, 16, v29
	v_and_b32_e32 v99, 0xffff0000, v29
	v_lshlrev_b32_e32 v102, 16, v28
	v_and_b32_e32 v103, 0xffff0000, v28
	v_pk_mul_f32 v[28:29], v[76:77], v[76:77]
	v_add_f32_e32 v32, v33, v32
	v_add_f32_e32 v28, v28, v32
	v_pk_mul_f32 v[122:123], v[102:103], v[102:103]
	v_add_f32_e32 v28, v29, v28
	v_add_f32_e32 v28, v122, v28
	v_pk_mul_f32 v[118:119], v[98:99], v[98:99]
	v_add_f32_e32 v28, v123, v28
	v_lshlrev_b32_e32 v94, 16, v30
	v_and_b32_e32 v95, 0xffff0000, v30
	v_add_f32_e32 v28, v118, v28
	v_pk_mul_f32 v[114:115], v[94:95], v[94:95]
	v_add_f32_e32 v28, v119, v28
	v_lshlrev_b32_e32 v90, 16, v31
	v_and_b32_e32 v91, 0xffff0000, v31
	v_add_f32_e32 v28, v114, v28
	v_pk_mul_f32 v[110:111], v[90:91], v[90:91]
	v_add_f32_e32 v28, v115, v28
	v_lshlrev_b32_e32 v40, 16, v44
	v_and_b32_e32 v41, 0xffff0000, v44
	v_add_f32_e32 v28, v110, v28
	v_pk_mul_f32 v[106:107], v[40:41], v[40:41]
	v_add_f32_e32 v28, v111, v28
	v_lshlrev_b32_e32 v84, 16, v45
	v_and_b32_e32 v85, 0xffff0000, v45
	v_add_f32_e32 v28, v106, v28
	v_pk_mul_f32 v[44:45], v[84:85], v[84:85]
	v_add_f32_e32 v28, v107, v28
	v_add_f32_e32 v28, v44, v28
	v_pk_mul_f32 v[34:35], v[82:83], v[82:83]
	v_add_f32_e32 v28, v45, v28
	v_add_f32_e32 v28, v34, v28
	v_pk_mul_f32 v[30:31], v[78:79], v[78:79]
	v_add_f32_e32 v28, v35, v28
	v_add_f32_e32 v28, v30, v28
	v_add_f32_e32 v30, v31, v28
	ds_bpermute_b32 v31, v176, v30
	s_waitcnt lgkmcnt(0)
; __device__ __forceinline__ unsigned pk2(float lo, float hi) { f32x2 v = {lo, hi}; bf16x2_t b = __builtin_convertvector(v, bf16x2_t); return __builtin_bit_cast(unsigned, b); }
; #define LOAD_TILE(ti, kreg, vreg) do { const int k0_ = TILE_K0(ti); const size_t grow_ = ((ti) < 4) ? (size_t)(M_ + b * LCTX + k0_) : (size_t)(b * SEQ + k0_); \
;         kreg = *(const u32x4*)(QKV + (grow_ + krow) * NQKV + 1024 + kvh * 64 + 8 * kch); vreg = *(const u32x4*)(QKV + (grow_ + lane) * NQKV + 1280 + kvh * 64 + 8 * w); } while (0)
; #define LOAD_TILE(ti, kreg, vreg) do { const int k0_ = TILE_K0(ti); const size_t grow_ = ((ti) < 4) ? (size_t)(M_ + b * LCTX + k0_) : (size_t)(b * SEQ + k0_); \
;         kreg = *(const u32x4*)(QKV + (grow_ + krow) * NQKV + 1024 + kvh * 64 + 8 * kch); vreg = *(const u32x4*)(QKV + (grow_ + lane) * NQKV + 1280 + kvh * 64 + 8 * w); } while (0)
;     ...
;             const float rstd = rsqrtf(ss * (1.0f / 64.0f) + 1e-6f);
; #pragma unroll
;             for (int d0 = 0; d0 < 4; ++d0)
; #pragma unroll
;                 for (int i = 0; i < 8; ++i) qf[d0][i] *= rstd * qgain[8 * (2 * d0 + hi) + i];
;             const float* rp = ROPE + (size_t)qrow * 64;
;             float qo[4][8];
; #pragma unroll
;             for (int d0 = 0; d0 < 2; ++d0)
; #pragma unroll
;                 for (int i = 0; i < 8; ++i) { const int j = 8 * (2 * d0 + hi) + i; const float cs = rp[j], sn = rp[32 + j];
;                     qo[d0][i] = qf[d0][i] * cs - qf[d0 + 2][i] * sn; qo[d0 + 2][i] = qf[d0][i] * sn + qf[d0 + 2][i] * cs; }
; #pragma unroll
;             for (int d0 = 0; d0 < 4; ++d0) { u32x4 pw; pw.x = pk2(qo[d0][0] * C2, qo[d0][1] * C2); pw.y = pk2(qo[d0][2] * C2, qo[d0][3] * C2); pw.z = pk2(qo[d0][4] * C2, qo[d0][5] * C2); pw.w = pk2(qo[d0][6] * C2, qo[d0][7] * C2);
;                 qr[d0] = __builtin_bit_cast(bf16x8, pw); }
;         }
;         float m_ref = sink[head] * 1.4426950408889634f; float l_run = hi ? 0.f : 1.f;
;         f32x16 o0 = {}, o1 = {}; f32x16 negm;
; #pragma unroll
;         for (int r = 0; r < 16; ++r) negm[r] = -m_ref;
;         u32x4 kreg, vreg, kreg2, vreg2, kreg3, vreg3;
;     ...
;         LOAD_TILE(0, kreg, vreg); STORE_TILE(0, 0); LOAD_TILE(1, kreg, vreg); LOAD_TILE(2, kreg2, vreg2); LOAD_TILE(3, kreg3, vreg3); __syncthreads();
	v_add_f32_e32 v30, v30, v31
	v_fmamk_f32 v42, v30, 0x3c800000, v180
	v_mul_f32_e32 v43, 0x4b800000, v42
	v_cmp_gt_f32_e32 vcc, s47, v42
	s_add_i32 s22, s39, 0x10040
	s_ashr_i32 s23, s22, 31
	v_cndmask_b32_e32 v42, v42, v43, vcc
	v_rsq_f32_e32 v104, v42
	global_load_dwordx4 v[42:45], v[72:73], off offset:80
	s_nop 0
	global_load_dwordx4 v[72:75], v[72:73], off offset:208
	v_mul_f32_e32 v146, 0x3fb8aa3b, v124
	ds_write_b128 v177, v[244:247]
	v_and_b32_e32 v200, 1, v152
	v_mul_u32_u24_e32 v200, 0x21e, v200
	v_add_u32_e32 v201, v200, v178
	s_mov_b64 s[92:93], vcc
	s_mov_b64 vcc, s[88:89]
	v_cndmask_b32_dpp v192, v250, v248, vcc quad_perm:[1,0,3,2] row_mask:0xf bank_mask:0xf
	v_cndmask_b32_dpp v193, v251, v249, vcc quad_perm:[1,0,3,2] row_mask:0xf bank_mask:0xf
	s_mov_b64 vcc, s[90:91]
	v_cndmask_b32_dpp v194, v248, v250, vcc quad_perm:[1,0,3,2] row_mask:0xf bank_mask:0xf
	v_cndmask_b32_dpp v195, v249, v251, vcc quad_perm:[1,0,3,2] row_mask:0xf bank_mask:0xf
	v_and_b32_e32 v196, 0xffff, v192
	v_lshl_or_b32 v196, v194, 16, v196
	v_lshrrev_b32_e32 v197, 16, v192
	v_and_or_b32 v197, v194, s70, v197
	v_and_b32_e32 v198, 0xffff, v193
	v_lshl_or_b32 v198, v195, 16, v198
	v_lshrrev_b32_e32 v199, 16, v193
	v_and_or_b32 v199, v195, s70, v199
	s_mov_b64 vcc, s[92:93]
	ds_write_b32 v201, v196 offset:18432
	ds_write_b32 v201, v197 offset:18568
	ds_write_b32 v201, v198 offset:18704
	ds_write_b32 v201, v199 offset:18840
	v_mul_f32_e32 v105, 0x45800000, v104
	v_cndmask_b32_e32 v104, v104, v105, vcc
	v_pk_mul_f32 v[36:37], v[36:37], v[104:105] op_sel_hi:[1,0]
	v_pk_mul_f32 v[8:9], v[8:9], v[104:105] op_sel_hi:[1,0]
	v_pk_mul_f32 v[36:37], v[36:37], v[100:101]
	v_pk_mul_f32 v[100:101], v[8:9], v[80:81]
	v_pk_mul_f32 v[8:9], v[10:11], v[104:105] op_sel_hi:[1,0]
	v_pk_mul_f32 v[0:1], v[0:1], v[104:105] op_sel_hi:[1,0]
	v_pk_mul_f32 v[76:77], v[8:9], v[76:77]
	v_pk_mul_f32 v[8:9], v[20:21], v[104:105] op_sel_hi:[1,0]
	v_pk_mul_f32 v[38:39], v[38:39], v[104:105] op_sel_hi:[1,0]
	v_pk_mul_f32 v[12:13], v[12:13], v[104:105] op_sel_hi:[1,0]
	v_pk_mul_f32 v[8:9], v[8:9], v[102:103]
	v_pk_mul_f32 v[10:11], v[22:23], v[104:105] op_sel_hi:[1,0]
	v_pk_mul_f32 v[112:113], v[0:1], v[82:83]
	v_pk_mul_f32 v[0:1], v[2:3], v[104:105] op_sel_hi:[1,0]
	v_pk_mul_f32 v[38:39], v[38:39], v[96:97]
	v_pk_mul_f32 v[24:25], v[24:25], v[104:105] op_sel_hi:[1,0]
	v_pk_mul_f32 v[96:97], v[12:13], v[86:87]
	v_pk_mul_f32 v[12:13], v[14:15], v[104:105] op_sel_hi:[1,0]
	v_pk_mul_f32 v[10:11], v[10:11], v[98:99]
	v_pk_mul_f32 v[78:79], v[0:1], v[78:79]
	v_pk_mul_f32 v[0:1], v[60:61], v[8:9]
	v_pk_mul_f32 v[24:25], v[24:25], v[92:93]
	v_pk_mul_f32 v[26:27], v[26:27], v[104:105] op_sel_hi:[1,0]
	v_pk_mul_f32 v[46:47], v[12:13], v[46:47]
	v_pk_mul_f32 v[12:13], v[16:17], v[104:105] op_sel_hi:[1,0]
	v_pk_fma_f32 v[114:115], v[68:69], v[36:37], v[0:1]
	v_pk_mul_f32 v[0:1], v[62:63], v[10:11]
	v_pk_mul_f32 v[26:27], v[26:27], v[88:89]
	v_pk_mul_f32 v[12:13], v[12:13], v[94:95]
	v_pk_mul_f32 v[14:15], v[18:19], v[104:105] op_sel_hi:[1,0]
	v_pk_fma_f32 v[116:117], v[70:71], v[38:39], v[0:1]
	v_pk_mul_f32 v[0:1], v[64:65], v[24:25]
	v_pk_mul_f32 v[14:15], v[14:15], v[90:91]
	v_pk_fma_f32 v[118:119], v[56:57], v[12:13], v[0:1]
	v_pk_mul_f32 v[0:1], v[26:27], v[66:67]
	v_pk_mul_f32 v[4:5], v[4:5], v[104:105] op_sel_hi:[1,0]
	v_pk_fma_f32 v[120:121], v[14:15], v[58:59], v[0:1]
	v_pk_mul_f32 v[0:1], v[68:69], v[8:9]
	v_pk_mul_f32 v[98:99], v[4:5], v[40:41]
	v_pk_fma_f32 v[0:1], v[60:61], v[36:37], v[0:1] neg_lo:[0,0,1] neg_hi:[0,0,1]
	v_pk_mul_f32 v[4:5], v[6:7], v[104:105] op_sel_hi:[1,0]
	v_pk_mul_f32 v[0:1], v[0:1], s[10:11] op_sel_hi:[1,0]
	v_pk_mul_f32 v[102:103], v[4:5], v[84:85]
	v_cvt_pk_bf16_f32 v80, v0, v1
	v_pk_mul_f32 v[0:1], v[70:71], v[10:11]
	v_lshl_add_u64 v[10:11], s[22:23], 0, v[154:155]
	v_pk_fma_f32 v[0:1], v[62:63], v[38:39], v[0:1] neg_lo:[0,0,1] neg_hi:[0,0,1]
	v_pk_mul_f32 v[16:17], v[102:103], v[54:55]
	v_pk_mul_f32 v[0:1], v[0:1], s[10:11] op_sel_hi:[1,0]
	v_pk_fma_f32 v[16:17], v[46:47], v[50:51], v[16:17] neg_lo:[0,0,1] neg_hi:[0,0,1]
	v_cvt_pk_bf16_f32 v81, v0, v1
	v_pk_mul_f32 v[0:1], v[12:13], v[64:65]
	v_mad_u64_u32 v[12:13], s[40:41], v10, s46, v[160:161]
	v_mad_i32_i24 v13, v11, s46, v13
	v_lshl_add_u64 v[10:11], v[12:13], 0, s[8:9]
	v_or_b32_e32 v12, s22, v144
	v_mad_i64_i32 v[12:13], s[22:23], v12, s46, v[160:161]
	s_add_i32 s22, s39, 0x10080
	v_lshl_add_u64 v[10:11], v[10:11], 0, v[168:169]
	v_lshl_add_u64 v[12:13], v[12:13], 0, s[8:9]
	s_ashr_i32 s23, s22, 31
	v_lshl_add_u64 v[12:13], v[12:13], 0, s[20:21]
	global_load_dwordx4 v[38:41], v[10:11], off offset:2048
	global_load_dwordx4 v[34:37], v[12:13], off offset:2560
	v_lshl_add_u64 v[10:11], s[22:23], 0, v[154:155]
	v_mad_u64_u32 v[12:13], s[40:41], v10, s46, v[160:161]
	v_mad_i32_i24 v13, v11, s46, v13
	v_lshl_add_u64 v[10:11], v[12:13], 0, s[8:9]
	v_or_b32_e32 v12, s22, v144
	v_mad_i64_i32 v[12:13], s[22:23], v12, s46, v[160:161]
	s_add_i32 s22, s39, 0x100c0
	v_lshl_add_u64 v[10:11], v[10:11], 0, v[168:169]
	v_lshl_add_u64 v[12:13], v[12:13], 0, s[8:9]
	s_ashr_i32 s23, s22, 31
	v_lshl_add_u64 v[12:13], v[12:13], 0, s[20:21]
	global_load_dwordx4 v[108:111], v[10:11], off offset:2048
	global_load_dwordx4 v[104:107], v[12:13], off offset:2560
	v_lshl_add_u64 v[10:11], s[22:23], 0, v[154:155]
	v_mad_u64_u32 v[12:13], s[40:41], v10, s46, v[160:161]
	v_mad_i32_i24 v13, v11, s46, v13
	v_lshl_add_u64 v[10:11], v[12:13], 0, s[8:9]
	v_or_b32_e32 v12, s22, v144
	v_mad_i64_i32 v[12:13], s[22:23], v12, s46, v[160:161]
	v_lshl_add_u64 v[10:11], v[10:11], 0, v[168:169]
	v_lshl_add_u64 v[12:13], v[12:13], 0, s[8:9]
	v_pk_fma_f32 v[0:1], v[24:25], v[56:57], v[0:1] neg_lo:[0,0,1] neg_hi:[0,0,1]
	v_lshl_add_u64 v[12:13], v[12:13], 0, s[20:21]
	global_load_dwordx4 v[88:91], v[10:11], off offset:2048
	global_load_dwordx4 v[92:95], v[12:13], off offset:2560
	v_pk_mul_f32 v[0:1], v[0:1], s[10:11] op_sel_hi:[1,0]
	s_waitcnt lgkmcnt(0)
	v_cvt_pk_bf16_f32 v82, v0, v1
	v_pk_mul_f32 v[0:1], v[14:15], v[66:67]
	s_barrier
; __device__ __forceinline__ unsigned pk2(float lo, float hi) { f32x2 v = {lo, hi}; bf16x2_t b = __builtin_convertvector(v, bf16x2_t); return __builtin_bit_cast(unsigned, b); }
;     ...
; #pragma unroll
;             for (int d0 = 0; d0 < 4; ++d0) { u32x4 pw; pw.x = pk2(qo[d0][0] * C2, qo[d0][1] * C2); pw.y = pk2(qo[d0][2] * C2, qo[d0][3] * C2); pw.z = pk2(qo[d0][4] * C2, qo[d0][5] * C2); pw.w = pk2(qo[d0][6] * C2, qo[d0][7] * C2);
;                 qr[d0] = __builtin_bit_cast(bf16x8, pw); }
;         }
;         float m_ref = sink[head] * 1.4426950408889634f; float l_run = hi ? 0.f : 1.f;
;         f32x16 o0 = {}, o1 = {}; f32x16 negm;
; #pragma unroll
;         for (int r = 0; r < 16; ++r) negm[r] = -m_ref;
;         u32x4 kreg, vreg, kreg2, vreg2, kreg3, vreg3;
	v_pk_fma_f32 v[0:1], v[26:27], v[58:59], v[0:1] neg_lo:[0,0,1] neg_hi:[0,0,1]
	ds_read_b128 v[56:59], v145
	v_pk_mul_f32 v[0:1], v[0:1], s[10:11] op_sel_hi:[1,0]
	ds_read_b128 v[60:63], v145 offset:4608
	ds_read_b128 v[64:67], v145 offset:32
	v_cvt_pk_bf16_f32 v83, v0, v1
	v_pk_mul_f32 v[0:1], v[98:99], v[52:53]
	v_pk_mul_f32 v[16:17], v[16:17], s[10:11] op_sel_hi:[1,0]
	v_pk_fma_f32 v[0:1], v[96:97], v[48:49], v[0:1] neg_lo:[0,0,1] neg_hi:[0,0,1]
	v_cvt_pk_bf16_f32 v85, v16, v17
	v_pk_mul_f32 v[0:1], v[0:1], s[10:11] op_sel_hi:[1,0]
	s_waitcnt vmcnt(6)
	v_pk_mul_f32 v[68:69], v[112:113], v[72:73]
	v_cvt_pk_bf16_f32 v84, v0, v1
	v_xor_b32_e32 v0, 0x80000000, v146
	v_mov_b32_e32 v1, v0
	v_mov_b32_e32 v2, v0
	v_mov_b32_e32 v3, v0
	v_mov_b32_e32 v4, v0
	v_mov_b32_e32 v5, v0
	v_mov_b32_e32 v6, v0
	v_mov_b32_e32 v7, v0
	v_mov_b32_e32 v8, v0
	v_mov_b32_e32 v9, v0
	v_mov_b32_e32 v10, v0
	v_mov_b32_e32 v11, v0
	v_mov_b32_e32 v12, v0
	v_mov_b32_e32 v13, v0
	v_mov_b32_e32 v14, v0
	v_mov_b32_e32 v15, v0
	v_pk_mul_f32 v[52:53], v[96:97], v[52:53]
	s_waitcnt lgkmcnt(2)
	v_mfma_f32_32x32x16_bf16 v[18:33], v[56:59], v[80:83], v[0:15]
	v_mov_b64_e32 v[16:17], v[14:15]
	ds_read_b128 v[56:59], v145 offset:4640
	s_nop 4
	v_mov_b64_e32 v[14:15], v[12:13]
	v_mov_b64_e32 v[12:13], v[10:11]
	v_mov_b64_e32 v[10:11], v[8:9]
	v_mov_b64_e32 v[8:9], v[6:7]
	v_mov_b64_e32 v[6:7], v[4:5]
	v_mov_b64_e32 v[4:5], v[2:3]
	v_mov_b64_e32 v[2:3], v[0:1]
	s_waitcnt lgkmcnt(2)
	s_nop 0
	v_mfma_f32_32x32x16_bf16 v[2:17], v[60:63], v[80:83], v[2:17]
	v_fma_f32 v60, v100, v42, -v68
	v_fma_f32 v61, v101, v43, -v69
	v_mul_f32_e64 v62, v46, v54
	v_mul_f32_e64 v63, v47, v55
	v_mul_f32_e64 v60, v60, s10
	v_mul_f32_e64 v61, v61, s10
	v_pk_mul_f32 v[46:47], v[114:115], s[10:11] op_sel_hi:[1,0]
	v_cvt_pk_bf16_f32 v86, v60, v61
	v_pk_mul_f32 v[60:61], v[78:79], v[74:75]
	v_cvt_pk_bf16_f32 v96, v46, v47
	v_pk_fma_f32 v[60:61], v[76:77], v[44:45], v[60:61] neg_lo:[0,0,1] neg_hi:[0,0,1]
	s_nop 0
	v_pk_mul_f32 v[60:61], v[60:61], s[10:11] op_sel_hi:[1,0]
	s_nop 0
	v_cvt_pk_bf16_f32 v87, v60, v61
	v_pk_fma_f32 v[60:61], v[98:99], v[48:49], v[52:53]
	ds_read_b128 v[46:49], v145 offset:64
	s_waitcnt lgkmcnt(2)
	v_mfma_f32_32x32x16_bf16 v[18:33], v[64:67], v[84:87], v[18:33]
	v_mul_f32_e64 v52, v116, s10
	v_mul_f32_e64 v53, v117, s10
	v_mul_f32_e64 v60, v60, s10
	v_mul_f32_e64 v61, v61, s10
	v_cvt_pk_bf16_f32 v97, v52, v53
	v_pk_mul_f32 v[52:53], v[118:119], s[10:11] op_sel_hi:[1,0]
	s_nop 0
	v_cvt_pk_bf16_f32 v98, v52, v53
	v_pk_mul_f32 v[52:53], v[120:121], s[10:11] op_sel_hi:[1,0]
	s_waitcnt lgkmcnt(1)
	v_mfma_f32_32x32x16_bf16 v[2:17], v[56:59], v[84:87], v[2:17]
	v_cvt_pk_bf16_f32 v99, v52, v53
	ds_read_b128 v[52:55], v145 offset:4672
	ds_read_b128 v[56:59], v145 offset:96
	s_waitcnt lgkmcnt(2)
	v_mfma_f32_32x32x16_bf16 v[18:33], v[46:49], v[96:99], v[18:33]
	v_mul_f32_e64 v48, v100, v72
	v_mul_f32_e64 v49, v101, v73
	v_fma_f32 v46, v102, v50, v62
	v_fma_f32 v47, v103, v51, v63
	v_fma_f32 v48, v112, v42, v48
	v_fma_f32 v49, v113, v43, v49
	v_pk_mul_f32 v[42:43], v[76:77], v[74:75]
	v_pk_mul_f32 v[46:47], v[46:47], s[10:11] op_sel_hi:[1,0]
	v_pk_fma_f32 v[50:51], v[78:79], v[44:45], v[42:43]
	ds_read_b128 v[42:45], v145 offset:4704
	s_waitcnt lgkmcnt(2)
	v_mfma_f32_32x32x16_bf16 v[2:17], v[52:55], v[96:99], v[2:17]
	v_cvt_pk_bf16_f32 v101, v46, v47
	v_mul_f32_e64 v46, v48, s10
	v_mul_f32_e64 v47, v49, s10
	v_cvt_pk_bf16_f32 v100, v60, v61
	v_cvt_pk_bf16_f32 v102, v46, v47
	v_pk_mul_f32 v[46:47], v[50:51], s[10:11] op_sel_hi:[1,0]
	s_nop 0
	v_cvt_pk_bf16_f32 v103, v46, v47
	s_waitcnt lgkmcnt(1)
	s_nop 0
	v_mfma_f32_32x32x16_bf16 v[18:33], v[56:59], v[100:103], v[18:33]
	s_waitcnt lgkmcnt(0)
	v_mfma_f32_32x32x16_bf16 v[2:17], v[42:45], v[100:103], v[2:17]
	s_nop 9
	v_max_f32_e32 v42, v19, v19
	v_max_f32_e32 v43, v20, v20
	v_max_f32_e32 v44, v21, v21
	v_max_f32_e32 v1, v3, v3
	v_max_f32_e32 v1, v42, v1
	v_max_f32_e32 v42, v4, v4
	v_max_f32_e32 v42, v43, v42
	v_max_f32_e32 v43, v5, v5
	v_max3_f32 v1, v18, v2, v1
	v_max_f32_e32 v43, v44, v43
	v_max3_f32 v1, v1, v42, v43
	v_max_f32_e32 v42, v6, v6
	v_max_f32_e32 v43, v22, v22
	v_max_f32_e32 v42, v43, v42
	v_max_f32_e32 v43, v7, v7
	v_max_f32_e32 v44, v23, v23
	v_max_f32_e32 v43, v44, v43
	v_max3_f32 v1, v1, v42, v43
	v_max_f32_e32 v42, v8, v8
	v_max_f32_e32 v43, v24, v24
	v_max_f32_e32 v42, v43, v42
	v_max_f32_e32 v43, v9, v9
	v_max_f32_e32 v44, v25, v25
	v_max_f32_e32 v43, v44, v43
	v_max3_f32 v1, v1, v42, v43
	v_max_f32_e32 v42, v10, v10
	v_max_f32_e32 v43, v26, v26
	v_max_f32_e32 v42, v43, v42
	v_max_f32_e32 v43, v11, v11
	v_max_f32_e32 v44, v27, v27
	v_max_f32_e32 v43, v44, v43
	v_max3_f32 v1, v1, v42, v43
	v_max_f32_e32 v42, v12, v12
	v_max_f32_e32 v43, v28, v28
	v_max_f32_e32 v42, v43, v42
	v_max_f32_e32 v43, v13, v13
	v_max_f32_e32 v44, v29, v29
	v_max_f32_e32 v43, v44, v43
	v_max3_f32 v1, v1, v42, v43
	v_max_f32_e32 v42, v14, v14
	v_max_f32_e32 v43, v30, v30
	v_max_f32_e32 v42, v43, v42
	v_max_f32_e32 v43, v15, v15
	v_max_f32_e32 v44, v31, v31
	v_max_f32_e32 v43, v44, v43
	v_max3_f32 v1, v1, v42, v43
	v_max_f32_e32 v42, v16, v16
	v_max_f32_e32 v43, v32, v32
	v_max_f32_e32 v42, v43, v42
	v_max_f32_e32 v43, v17, v17
	v_max_f32_e32 v44, v33, v33
	v_max_f32_e32 v43, v44, v43
	v_max3_f32 v1, v1, v42, v43
	ds_bpermute_b32 v42, v176, v1
	s_waitcnt lgkmcnt(0)
	v_max_f32_e32 v42, v42, v42
	v_max_f32_e32 v1, v1, v42
	v_cmp_lt_f32_e32 vcc, s52, v1
	s_cmp_eq_u64 vcc, 0
	s_cselect_b64 s[22:23], -1, 0
	s_cbranch_vccz .LBB0_505
	v_max_f32_e32 v0, v1, v1
	v_max_f32_e32 v42, 0, v0
	v_exp_f32_e64 v44, -v42
	v_add_f32_e32 v146, v146, v42
	v_xor_b32_e32 v0, 0x80000000, v146
	v_pk_add_f32 v[18:19], v[18:19], v[42:43] op_sel_hi:[1,0] neg_lo:[0,1] neg_hi:[0,1]
	v_pk_add_f32 v[2:3], v[2:3], v[42:43] op_sel_hi:[1,0] neg_lo:[0,1] neg_hi:[0,1]
	v_pk_add_f32 v[20:21], v[20:21], v[42:43] op_sel_hi:[1,0] neg_lo:[0,1] neg_hi:[0,1]
	v_pk_add_f32 v[4:5], v[4:5], v[42:43] op_sel_hi:[1,0] neg_lo:[0,1] neg_hi:[0,1]
	v_pk_add_f32 v[22:23], v[22:23], v[42:43] op_sel_hi:[1,0] neg_lo:[0,1] neg_hi:[0,1]
	v_pk_add_f32 v[6:7], v[6:7], v[42:43] op_sel_hi:[1,0] neg_lo:[0,1] neg_hi:[0,1]
	v_pk_add_f32 v[24:25], v[24:25], v[42:43] op_sel_hi:[1,0] neg_lo:[0,1] neg_hi:[0,1]
	v_pk_add_f32 v[8:9], v[8:9], v[42:43] op_sel_hi:[1,0] neg_lo:[0,1] neg_hi:[0,1]
	v_pk_add_f32 v[26:27], v[26:27], v[42:43] op_sel_hi:[1,0] neg_lo:[0,1] neg_hi:[0,1]
	v_pk_add_f32 v[10:11], v[10:11], v[42:43] op_sel_hi:[1,0] neg_lo:[0,1] neg_hi:[0,1]
	v_pk_add_f32 v[28:29], v[28:29], v[42:43] op_sel_hi:[1,0] neg_lo:[0,1] neg_hi:[0,1]
	v_pk_add_f32 v[12:13], v[12:13], v[42:43] op_sel_hi:[1,0] neg_lo:[0,1] neg_hi:[0,1]
	v_pk_add_f32 v[30:31], v[30:31], v[42:43] op_sel_hi:[1,0] neg_lo:[0,1] neg_hi:[0,1]
	v_pk_add_f32 v[14:15], v[14:15], v[42:43] op_sel_hi:[1,0] neg_lo:[0,1] neg_hi:[0,1]
	v_pk_add_f32 v[32:33], v[32:33], v[42:43] op_sel_hi:[1,0] neg_lo:[0,1] neg_hi:[0,1]
	v_pk_add_f32 v[16:17], v[16:17], v[42:43] op_sel_hi:[1,0] neg_lo:[0,1] neg_hi:[0,1]
	v_pk_mul_f32 v[42:43], v[150:151], v[44:45] op_sel_hi:[1,0]
	s_branch .LBB0_506

; #define LOAD_TILE(ti, kreg, vreg) do { const int k0_ = TILE_K0(ti); const size_t grow_ = ((ti) < 4) ? (size_t)(M_ + b * LCTX + k0_) : (size_t)(b * SEQ + k0_); \
;         kreg = *(const u32x4*)(QKV + (grow_ + krow) * NQKV + 1024 + kvh * 64 + 8 * kch); vreg = *(const u32x4*)(QKV + (grow_ + lane) * NQKV + 1280 + kvh * 64 + 8 * w); } while (0)
; #define LOAD_TILE(ti, kreg, vreg) do { const int k0_ = TILE_K0(ti); const size_t grow_ = ((ti) < 4) ? (size_t)(M_ + b * LCTX + k0_) : (size_t)(b * SEQ + k0_); \
;         kreg = *(const u32x4*)(QKV + (grow_ + krow) * NQKV + 1024 + kvh * 64 + 8 * kch); vreg = *(const u32x4*)(QKV + (grow_ + lane) * NQKV + 1280 + kvh * 64 + 8 * w); } while (0)
; #define STAGE_NEXT(ti, vnext) do { if ((ti) + 1 < ntiles) STORE_TILE(((ti) + 1) & 1, vnext); \
;         kreg = kreg2; vreg = vreg2; kreg2 = kreg3; vreg2 = vreg3; \
;         if ((ti) + 4 < ntiles) LOAD_TILE((ti) + 4, kreg3, vreg3); } while (0)
;     ...
;         bf16x8 pa[4];
;         LOAD_TILE(0, kreg, vreg); STORE_TILE(0, 0); LOAD_TILE(1, kreg, vreg); LOAD_TILE(2, kreg2, vreg2); LOAD_TILE(3, kreg3, vreg3); __syncthreads();
;         {
;             QK_MAX(0, 0)
;             EXP_PACK();
;             if (resc) { _Pragma("unroll") for (int r = 0; r < 16; ++r) { o0[r] *= fres; o1[r] *= fres; } }
;             STAGE_NEXT(0, 1);
;             __syncthreads();
.LBB0_506:
	v_exp_f32_e32 v1, v18
	v_exp_f32_e32 v46, v2
	v_exp_f32_e32 v47, v19
	v_exp_f32_e32 v48, v3
	v_exp_f32_e32 v49, v20
	v_add_f32_e32 v2, v46, v1
	v_exp_f32_e32 v50, v4
	v_add_f32_e32 v2, 0, v2
	v_add_f32_e32 v3, v48, v47
	v_exp_f32_e32 v51, v21
	v_exp_f32_e32 v52, v5
	v_add_f32_e32 v18, v3, v2
	v_exp_f32_e32 v3, v22
	v_exp_f32_e32 v5, v6
	v_exp_f32_e32 v2, v23
	v_exp_f32_e32 v4, v7
	v_add_f32_e32 v19, v50, v49
	v_add_f32_e32 v6, v19, v18
	v_add_f32_e32 v7, v52, v51
	v_add_f32_e32 v18, v7, v6
	v_pk_add_f32 v[6:7], v[4:5], v[2:3]
	v_exp_f32_e32 v19, v24
	v_add_f32_e32 v7, v7, v18
	v_exp_f32_e32 v21, v8
	v_exp_f32_e32 v18, v25
	v_exp_f32_e32 v20, v9
	v_add_f32_e32 v8, v6, v7
	v_exp_f32_e32 v9, v26
	v_exp_f32_e32 v23, v10
	v_pk_add_f32 v[6:7], v[20:21], v[18:19]
	v_exp_f32_e32 v22, v11
	v_add_f32_e32 v7, v7, v8
	v_exp_f32_e32 v8, v27
	s_lshl_b32 s8, s25, 6
	s_sub_i32 s25, 0x80, s13
	s_lshl_b32 s56, s38, 6
	s_and_b32 s39, s44, 0x1fc0
	s_ashr_i32 s33, s25, 6
	s_cmpk_lt_u32 s13, 0x80
	v_pk_mov_b32 v[10:11], v[18:19], v[18:19] op_sel:[1,0]
	v_pk_mov_b32 v[18:19], v[20:21], v[20:21] op_sel:[1,0]
	v_add_f32_e32 v20, v6, v7
	v_pk_add_f32 v[6:7], v[22:23], v[8:9]
	s_cselect_b32 s57, s33, 0
	s_sub_i32 s33, 0x2040, s13
	v_add_f32_e32 v7, v7, v20
	v_exp_f32_e32 v21, v28
	v_exp_f32_e32 v25, v12
	v_exp_f32_e32 v20, v29
	v_exp_f32_e32 v24, v13
	s_lshr_b32 s33, s33, 6
	s_cmpk_gt_u32 s13, 0x1f40
	s_cselect_b32 s33, s33, 4
	s_sub_i32 s58, s33, s57
	v_pk_mov_b32 v[12:13], v[22:23], v[22:23] op_sel:[1,0]
	v_add_f32_e32 v22, v6, v7
	v_pk_add_f32 v[6:7], v[24:25], v[20:21]
	s_lshl_b32 s33, s57, 6
	v_add_f32_e32 v7, v7, v22
	v_exp_f32_e32 v23, v30
	v_exp_f32_e32 v27, v14
	v_exp_f32_e32 v22, v31
	v_exp_f32_e32 v26, v15
	s_add_i32 s24, s24, s33
	s_add_i32 s13, s13, s24
	s_add_i32 s40, s13, 0xffffff80
	s_ashr_i32 s41, s40, 31
	v_pk_mov_b32 v[14:15], v[20:21], v[20:21] op_sel:[1,0]
	v_pk_mov_b32 v[20:21], v[24:25], v[24:25] op_sel:[1,0]
	v_add_f32_e32 v24, v6, v7
	v_pk_add_f32 v[6:7], v[26:27], v[22:23]
	v_exp_f32_e32 v29, v16
	v_or_b32_e32 v16, s40, v144
	v_mov_b64_e32 v[30:31], s[4:5]
	v_lshl_add_u64 v[44:45], s[40:41], 0, v[154:155]
	v_add_f32_e32 v7, v7, v24
	v_exp_f32_e32 v25, v32
	v_exp_f32_e32 v24, v33
	v_mad_i64_i32 v[32:33], s[62:63], v16, s46, v[30:31]
	s_lshl_b32 s8, s8, 1
	v_mad_u64_u32 v[30:31], s[40:41], v44, s46, v[30:31]
	v_lshl_add_u64 v[32:33], v[32:33], 0, s[8:9]
	s_mov_b32 s13, s9
	v_mad_i32_i24 v31, v45, s46, v31
	v_lshl_add_u64 v[32:33], v[32:33], 0, s[12:13]
	v_lshl_add_u64 v[30:31], v[30:31], 0, s[8:9]
	v_mov_b32_e32 v165, v147
	v_lshl_add_u64 v[30:31], v[30:31], 0, v[164:165]
	global_load_dwordx4 v[112:115], v[32:33], off offset:2560
	global_load_dwordx4 v[116:119], v[30:31], off offset:2048
	v_exp_f32_e32 v28, v17
	v_pk_mov_b32 v[16:17], v[22:23], v[22:23] op_sel:[1,0]
	v_pk_mov_b32 v[22:23], v[26:27], v[26:27] op_sel:[1,0]
	v_add_f32_e32 v26, v6, v7
	v_pk_add_f32 v[6:7], v[28:29], v[24:25]
	v_cvt_pk_bf16_f32 v130, v16, v17
	v_add_f32_e32 v7, v7, v26
	v_cndmask_b32_e64 v16, v42, 0, s[22:23]
	s_add_i32 s13, s58, 4
	v_pk_mov_b32 v[24:25], v[24:25], v[24:25] op_sel:[1,0]
	v_pk_mov_b32 v[26:27], v[28:29], v[28:29] op_sel:[1,0]
	v_add_f32_e32 v6, v6, v7
	v_mov_b32_e32 v30, v16
	v_mov_b32_e32 v31, v16
	s_add_u32 s22, s42, s8
	v_pk_mov_b32 v[2:3], v[2:3], v[2:3] op_sel:[1,0]
	v_pk_mov_b32 v[4:5], v[4:5], v[4:5] op_sel:[1,0]
	v_pk_mov_b32 v[8:9], v[8:9], v[8:9] op_sel:[1,0]
	v_add_f32_e32 v165, v43, v6
	v_cvt_pk_bf16_f32 v132, v1, v47
	v_cvt_pk_bf16_f32 v131, v24, v25
	v_cvt_pk_bf16_f32 v124, v46, v48
	v_cvt_pk_bf16_f32 v127, v18, v19
	v_cvt_pk_bf16_f32 v121, v20, v21
	v_cvt_pk_bf16_f32 v122, v22, v23
	v_cvt_pk_bf16_f32 v123, v26, v27
	v_mov_b32_e32 v17, v16
	v_mov_b32_e32 v18, v16
	v_mov_b32_e32 v19, v16
	v_mov_b32_e32 v20, v16
	v_mov_b32_e32 v21, v16
	v_mov_b32_e32 v22, v16
	v_mov_b32_e32 v23, v16
	v_mov_b32_e32 v24, v16
	v_mov_b32_e32 v25, v16
	v_mov_b32_e32 v26, v16
	v_mov_b32_e32 v27, v16
	v_mov_b32_e32 v28, v16
	v_mov_b32_e32 v29, v16
	s_waitcnt vmcnt(7)
	ds_write_b128 v177, v[38:41] offset:9216
	s_waitcnt vmcnt(6)
	v_and_b32_e32 v200, 1, v152
	v_mul_u32_u24_e32 v200, 0x21e, v200
	v_add_u32_e32 v201, v200, v178
	s_mov_b64 s[92:93], vcc
	s_mov_b64 vcc, s[88:89]
	v_cndmask_b32_dpp v192, v36, v34, vcc quad_perm:[1,0,3,2] row_mask:0xf bank_mask:0xf
	v_cndmask_b32_dpp v193, v37, v35, vcc quad_perm:[1,0,3,2] row_mask:0xf bank_mask:0xf
	s_mov_b64 vcc, s[90:91]
	v_cndmask_b32_dpp v194, v34, v36, vcc quad_perm:[1,0,3,2] row_mask:0xf bank_mask:0xf
	v_cndmask_b32_dpp v195, v35, v37, vcc quad_perm:[1,0,3,2] row_mask:0xf bank_mask:0xf
	v_and_b32_e32 v196, 0xffff, v192
	v_lshl_or_b32 v196, v194, 16, v196
	v_lshrrev_b32_e32 v197, 16, v192
	v_and_or_b32 v197, v194, s70, v197
	v_and_b32_e32 v198, 0xffff, v193
	v_lshl_or_b32 v198, v195, 16, v198
	v_lshrrev_b32_e32 v199, 16, v193
	v_and_or_b32 v199, v195, s70, v199
	s_mov_b64 vcc, s[92:93]
	ds_write_b32 v201, v196 offset:27136
	ds_write_b32 v201, v197 offset:27272
	ds_write_b32 v201, v198 offset:27408
	ds_write_b32 v201, v199 offset:27544
	s_addc_u32 s23, s43, 0
	s_add_i32 s24, s24, s39
	v_mov_b64_e32 v[46:47], v[30:31]
	v_ashrrev_i32_e32 v171, 31, v170
	s_mov_b32 s25, 0
	v_cvt_pk_bf16_f32 v133, v49, v51
	v_cvt_pk_bf16_f32 v134, v2, v3
	v_cvt_pk_bf16_f32 v135, v10, v11
	v_cvt_pk_bf16_f32 v128, v8, v9
	v_cvt_pk_bf16_f32 v129, v14, v15
	v_cvt_pk_bf16_f32 v125, v50, v52
	v_cvt_pk_bf16_f32 v126, v4, v5
	v_cvt_pk_bf16_f32 v120, v12, v13
	s_mov_b32 s38, 1
	v_lshl_add_u64 v[172:173], v[158:159], 0, s[8:9]
	s_sub_i32 s24, s24, 64
	v_subrev_u32_e32 v167, s33, v179
	v_mov_b64_e32 v[44:45], v[28:29]
	v_mov_b64_e32 v[42:43], v[26:27]
	v_mov_b64_e32 v[40:41], v[24:25]
	v_mov_b64_e32 v[38:39], v[22:23]
	v_mov_b64_e32 v[36:37], v[20:21]
	v_mov_b64_e32 v[34:35], v[18:19]
	v_mov_b64_e32 v[32:33], v[16:17]
	s_mov_b32 s62, 0
	v_mov_b32_e32 v1, v0
	v_mov_b32_e32 v2, v0
	v_mov_b32_e32 v3, v0
	v_mov_b32_e32 v4, v0
	v_mov_b32_e32 v5, v0
	v_mov_b32_e32 v6, v0
	v_mov_b32_e32 v7, v0
	v_mov_b32_e32 v8, v0
	v_mov_b32_e32 v9, v0
	v_mov_b32_e32 v10, v0
	v_mov_b32_e32 v11, v0
	v_mov_b32_e32 v12, v0
	v_mov_b32_e32 v13, v0
	v_mov_b32_e32 v14, v0
	v_mov_b32_e32 v15, v0
	s_waitcnt lgkmcnt(0)
	s_barrier

.LBB0_519:
	s_add_i32 s33, s59, 1
	s_cmp_lg_u32 s59, 2
	s_cselect_b32 s38, s33, 0
	s_cmp_ge_i32 s8, s13
	s_cbranch_scc1 .LBB0_521
	s_bitcmp1_b32 s25, 0
	s_cselect_b32 s25, 0x2400, 0
	v_add_u32_e32 v120, s25, v177
	s_mul_i32 s25, s38, 0x2200
	s_waitcnt vmcnt(5)
	ds_write_b128 v120, v[108:111]
	v_add_u32_e32 v108, s25, v178
	s_waitcnt vmcnt(4)
	v_and_b32_e32 v200, 1, v152
	v_mul_u32_u24_e32 v200, 0x21e, v200
	v_add_u32_e32 v201, v200, v108
	s_mov_b64 s[92:93], vcc
	s_mov_b64 vcc, s[88:89]
	v_cndmask_b32_dpp v192, v106, v104, vcc quad_perm:[1,0,3,2] row_mask:0xf bank_mask:0xf
	v_cndmask_b32_dpp v193, v107, v105, vcc quad_perm:[1,0,3,2] row_mask:0xf bank_mask:0xf
	s_mov_b64 vcc, s[90:91]
	v_cndmask_b32_dpp v194, v104, v106, vcc quad_perm:[1,0,3,2] row_mask:0xf bank_mask:0xf
	v_cndmask_b32_dpp v195, v105, v107, vcc quad_perm:[1,0,3,2] row_mask:0xf bank_mask:0xf
	v_and_b32_e32 v196, 0xffff, v192
	v_lshl_or_b32 v196, v194, 16, v196
	v_lshrrev_b32_e32 v197, 16, v192
	v_and_or_b32 v197, v194, s70, v197
	v_and_b32_e32 v198, 0xffff, v193
	v_lshl_or_b32 v198, v195, 16, v198
	v_lshrrev_b32_e32 v199, 16, v193
	v_and_or_b32 v199, v195, s70, v199
	s_mov_b64 vcc, s[92:93]
	ds_write_b32 v201, v196 offset:18432
	ds_write_b32 v201, v197 offset:18568
	ds_write_b32 v201, v198 offset:18704
	ds_write_b32 v201, v199 offset:18840
